# GEMM prologue stages K-tile 1 together with K-tile 0 and waits for K-tile 0 only (one DMA round trip less per GEMM call)
# speedup vs baseline: 1.0047x; 1.0047x over previous
; #define PG8_STAGE(bufoff, gbase, voff) do { _Pragma("unroll") for (int _i = 0; _i < 2; ++_i) \
;         __builtin_amdgcn_global_load_lds((const unsigned*)((const char*)(gbase) + (voff)[_i]), (LAS unsigned*)(lds + (bufoff) + ldsw + _i * 8192), 16, 0, 0); } while (0)
; #define PG8_WAIT_V(n) asm volatile("s_waitcnt vmcnt(" #n ")" ::: "memory")
; #define PG8_BAR __builtin_amdgcn_s_barrier()
; template <class Epi, class AMap>
; __device__ __forceinline__ void gemm_phase(LAS unsigned char* lds, const AMap am, const int lda, const h16* Bt, const int ldb, const int M, const int N, const int K, const Epi& E) {
;     ...
;     PG8_STAGE(PG8_SB(0, 0), cB, voffB); PG8_STAGE(PG8_SA(0, 0), cA, voffA); PG8_STAGE(PG8_SB(0, 1), cB + hstepB, voffB); PG8_STAGE(PG8_SA(0, 1), cA + hstepA, voffA);
;     if (wr == 1) PG8_BAR;
;     PG8_WAIT_V(4); PG8_BAR;
;     PG8_STAGE(PG8_SB(1, 0), cB + kstep, voffB); PG8_STAGE(PG8_SA(1, 0), cA + kstep, voffA); PG8_STAGE(PG8_SB(1, 1), cB + hstepB + kstep, voffB);
;     PG8_WAIT_V(6); PG8_BAR;
.LBB0_49:
	v_lshrrev_b32_e32 v20, 1, v10
	s_lshr_b32 s20, s20, 2
	v_and_b32_e32 v20, 24, v20
	s_lshl_b32 s0, s0, 5
	s_sext_i32_i8 s50, s20
	v_and_b32_e32 v11, 15, v10
	v_lshlrev_b32_e32 v21, 1, v20
	v_lshlrev_b32_e32 v10, 2, v10
	s_and_b32 s20, s0, 0x60
	v_lshl_add_u64 v[12:13], s[26:27], 0, v[0:1]
	v_mov_b32_e32 v135, v1
	v_lshl_or_b32 v146, s1, 6, v11
	v_lshl_or_b32 v11, v11, 6, v21
	s_lshl_b32 s1, s1, 13
	v_and_b32_e32 v10, 32, v10
	s_lshl_b32 s0, s20, 7
	v_lshl_add_u64 v[14:15], s[26:27], 0, v[134:135]
	v_mov_b32_e32 v131, v1
	v_bitop3_b32 v21, v11, s1, v10 bitop3:0xde
	v_bitop3_b32 v147, v11, s0, v10 bitop3:0xde
	s_add_i32 m0, s63, 0x18000
	v_lshl_add_u64 v[10:11], v[12:13], 0, s[92:93]
	v_lshl_add_u64 v[16:17], s[22:23], 0, v[130:131]
	v_mov_b32_e32 v133, v1
	global_load_lds_dwordx4 v[10:11], off
	v_lshl_add_u64 v[10:11], v[14:15], 0, s[92:93]
	s_add_i32 m0, s63, 0x1a000
	s_add_i32 s69, s63, 0x8000
	s_add_i32 s70, s63, 0xa000
	v_lshl_add_u64 v[18:19], s[22:23], 0, v[132:133]
	global_load_lds_dwordx4 v[10:11], off
	v_lshl_add_u64 v[10:11], v[16:17], 0, s[92:93]
	s_mov_b32 m0, s69
	s_add_u32 s0, s26, 0x158080
	global_load_lds_dwordx4 v[10:11], off
	v_lshl_add_u64 v[10:11], v[18:19], 0, s[92:93]
	s_mov_b32 m0, s70
	s_addc_u32 s1, s27, 0
	global_load_lds_dwordx4 v[10:11], off
	s_add_i32 m0, s63, 0x1c000
	v_lshl_add_u64 v[10:11], s[0:1], 0, v[0:1]
	global_load_lds_dwordx4 v[10:11], off
	v_lshl_add_u64 v[10:11], s[0:1], 0, v[134:135]
	s_add_i32 m0, s63, 0x1e000
	s_mov_b32 s4, 0x15800
	global_load_lds_dwordx4 v[10:11], off
	s_waitcnt vmcnt(6)
	s_barrier
	v_lshrrev_b32_e32 v10, 1, v2
	v_mul_lo_u32 v2, v4, s3
	v_mad_u64_u32 v[10:11], s[0:1], v10, s4, v[2:3]
	v_or_b32_e32 v2, v10, v3
	v_add_lshl_u32 v2, v2, v5, 1
	v_mov_b32_e32 v3, v1
	s_mov_b64 s[6:7], 0x158080
	v_lshl_add_u64 v[136:137], v[2:3], 0, s[6:7]
	v_lshrrev_b32_e32 v3, 1, v6
	v_mul_lo_u32 v2, v8, s3
	v_mad_u64_u32 v[2:3], s[0:1], v3, s4, v[2:3]
	s_waitcnt vmcnt(6)
	v_or_b32_e32 v2, v2, v7
	v_add_lshl_u32 v2, v2, v9, 1
	v_mov_b32_e32 v3, v1
	v_or_b32_e32 v148, s20, v20
	v_lshl_add_u64 v[138:139], v[2:3], 0, s[6:7]
	s_mov_b32 s71, 0
	v_add_u32_e32 v149, 0, v21
	s_mov_b64 s[6:7], s[40:41]
	s_barrier

; #define PG8_STAGE(bufoff, gbase, voff) do { _Pragma("unroll") for (int _i = 0; _i < 2; ++_i) \
;         __builtin_amdgcn_global_load_lds((const unsigned*)((const char*)(gbase) + (voff)[_i]), (LAS unsigned*)(lds + (bufoff) + ldsw + _i * 8192), 16, 0, 0); } while (0)
; #define PG8_WAIT_V(n) asm volatile("s_waitcnt vmcnt(" #n ")" ::: "memory")
; #define PG8_BAR __builtin_amdgcn_s_barrier()
; template <class Epi, class AMap>
; __device__ __forceinline__ void gemm_phase(LAS unsigned char* lds, const AMap am, const int lda, const h16* Bt, const int ldb, const int M, const int N, const int K, const Epi& E) {
;     ...
;     PG8_STAGE(PG8_SB(0, 0), cB, voffB); PG8_STAGE(PG8_SA(0, 0), cA, voffA); PG8_STAGE(PG8_SB(0, 1), cB + hstepB, voffB); PG8_STAGE(PG8_SA(0, 1), cA + hstepA, voffA);
;     if (wr == 1) PG8_BAR;
;     PG8_WAIT_V(4); PG8_BAR;
;     PG8_STAGE(PG8_SB(1, 0), cB + kstep, voffB); PG8_STAGE(PG8_SA(1, 0), cA + kstep, voffA); PG8_STAGE(PG8_SB(1, 1), cB + hstepB + kstep, voffB);
;     PG8_WAIT_V(6); PG8_BAR;
.LBB0_87:
	s_lshl_b32 s0, s0, 5
	s_and_b32 s0, s0, 0x60
	s_lshl_b32 s51, s1, 6
	s_lshl_b32 s1, s1, 13
	s_lshl_b32 s29, s0, 7
	s_add_u32 s8, s74, 0x5600
	s_addc_u32 s9, s75, 0
	s_add_u32 s70, s74, 0xac00
	s_addc_u32 s71, s75, 0
	s_add_i32 m0, s81, 0x18000
	v_lshl_add_u64 v[8:9], v[8:9], 0, s[92:93]
	global_load_lds_dwordx4 v[8:9], off
	v_lshl_add_u64 v[6:7], v[6:7], 0, s[92:93]
	s_add_i32 m0, s81, 0x1a000
	s_add_i32 s89, s81, 0x8000
	s_add_i32 s35, s81, 0xa000
	global_load_lds_dwordx4 v[6:7], off
	v_lshl_add_u64 v[4:5], v[4:5], 0, s[92:93]
	s_mov_b32 m0, s89
	s_add_u32 s20, s48, 0x80080
	global_load_lds_dwordx4 v[4:5], off
	v_lshl_add_u64 v[2:3], v[2:3], 0, s[92:93]
	s_mov_b32 m0, s35
	s_addc_u32 s21, s49, 0
	global_load_lds_dwordx4 v[2:3], off
	s_add_i32 m0, s81, 0x1c000
	v_lshl_add_u64 v[2:3], s[20:21], 0, v[0:1]
	global_load_lds_dwordx4 v[2:3], off
	v_lshl_add_u64 v[2:3], s[20:21], 0, v[162:163]
	s_add_i32 m0, s81, 0x1e000
	v_and_b32_e32 v168, 15, v10
	global_load_lds_dwordx4 v[2:3], off
	s_waitcnt vmcnt(6)
	s_barrier
	v_lshrrev_b32_e32 v2, 1, v10
	v_and_b32_e32 v2, 24, v2
	v_lshlrev_b32_e32 v3, 1, v2
	v_lshlrev_b32_e32 v4, 2, v10
	v_or_b32_e32 v194, s0, v2
	v_lshlrev_b32_e32 v2, 15, v15
	v_lshl_or_b32 v3, v168, 6, v3
	v_and_b32_e32 v4, 32, v4
	v_and_b32_e32 v2, 0xffff0000, v2
	v_bitop3_b32 v5, v3, s1, v4 bitop3:0xde
	v_bitop3_b32 v169, v3, s29, v4 bitop3:0xde
	v_lshl_add_u32 v2, v14, 12, v2
	v_and_b32_e32 v3, 1, v15
	v_lshl_or_b32 v2, v3, 6, v2
	v_lshl_add_u32 v172, v16, 1, v2
	v_lshlrev_b32_e32 v2, 15, v11
	v_and_b32_e32 v2, 0xffff0000, v2
	s_waitcnt vmcnt(6)
	v_lshl_add_u32 v2, v12, 12, v2
	v_and_b32_e32 v3, 1, v11
	v_lshl_or_b32 v2, v3, 6, v2
	s_sext_i32_i16 s23, s24
	s_mov_b32 s24, 0
	v_cmp_eq_u32_e64 s[38:39], 0, v168
	v_cmp_lt_u32_e64 s[40:41], 1, v168
	v_cmp_gt_u32_e64 s[42:43], 2, v168
	v_cmp_lt_u32_e64 s[44:45], 13, v168
	v_add_u32_e32 v170, -14, v168
	v_mov_b32_e32 v171, v1
	v_mov_b32_e32 v173, v1
	v_lshl_add_u32 v174, v13, 1, v2
	v_mov_b32_e32 v175, v1
	v_add_u32_e32 v195, 0, v5
	s_barrier
	s_branch .LBB0_89

; #define PG8_STAGE(bufoff, gbase, voff) do { _Pragma("unroll") for (int _i = 0; _i < 2; ++_i) \
;         __builtin_amdgcn_global_load_lds((const unsigned*)((const char*)(gbase) + (voff)[_i]), (LAS unsigned*)(lds + (bufoff) + ldsw + _i * 8192), 16, 0, 0); } while (0)
; #define PG8_WAIT_V(n) asm volatile("s_waitcnt vmcnt(" #n ")" ::: "memory")
; #define PG8_BAR __builtin_amdgcn_s_barrier()
; template <class Epi, class AMap>
; __device__ __forceinline__ void gemm_phase(LAS unsigned char* lds, const AMap am, const int lda, const h16* Bt, const int ldb, const int M, const int N, const int K, const Epi& E) {
;     ...
;     PG8_STAGE(PG8_SB(0, 0), cB, voffB); PG8_STAGE(PG8_SA(0, 0), cA, voffA); PG8_STAGE(PG8_SB(0, 1), cB + hstepB, voffB); PG8_STAGE(PG8_SA(0, 1), cA + hstepA, voffA);
;     if (wr == 1) PG8_BAR;
;     PG8_WAIT_V(4); PG8_BAR;
;     PG8_STAGE(PG8_SB(1, 0), cB + kstep, voffB); PG8_STAGE(PG8_SA(1, 0), cA + kstep, voffA); PG8_STAGE(PG8_SB(1, 1), cB + hstepB + kstep, voffB);
;     PG8_WAIT_V(6); PG8_BAR;
.LBB0_139:
	v_lshrrev_b32_e32 v18, 1, v8
	v_and_b32_e32 v18, 24, v18
	v_and_b32_e32 v9, 15, v8
	v_lshlrev_b32_e32 v19, 1, v18
	v_lshlrev_b32_e32 v8, 2, v8
	s_sext_i32_i8 s35, s0
	v_lshl_or_b32 v146, s20, 6, v9
	v_lshl_or_b32 v9, v9, 6, v19
	s_lshl_b32 s0, s20, 13
	v_and_b32_e32 v8, 32, v8
	v_bitop3_b32 v19, v9, s0, v8 bitop3:0xde
	s_lshl_b32 s0, s1, 5
	s_and_b32 s20, s0, 0x60
	v_lshl_add_u64 v[10:11], s[46:47], 0, v[0:1]
	v_mov_b32_e32 v135, v1
	s_lshl_b32 s0, s20, 7
	v_lshl_add_u64 v[12:13], s[46:47], 0, v[134:135]
	v_mov_b32_e32 v131, v1
	v_bitop3_b32 v147, v9, s0, v8 bitop3:0xde
	s_add_i32 m0, s23, 0x18000
	v_lshl_add_u64 v[8:9], v[10:11], 0, s[92:93]
	v_lshl_add_u64 v[14:15], s[26:27], 0, v[130:131]
	v_mov_b32_e32 v133, v1
	global_load_lds_dwordx4 v[8:9], off
	v_lshl_add_u64 v[8:9], v[12:13], 0, s[92:93]
	s_add_i32 m0, s23, 0x1a000
	s_add_i32 s74, s23, 0x8000
	s_add_i32 s75, s23, 0xa000
	v_lshl_add_u64 v[16:17], s[26:27], 0, v[132:133]
	global_load_lds_dwordx4 v[8:9], off
	v_lshl_add_u64 v[8:9], v[14:15], 0, s[92:93]
	s_mov_b32 m0, s74
	s_add_u32 s0, s46, 0x80080
	global_load_lds_dwordx4 v[8:9], off
	v_lshl_add_u64 v[8:9], v[16:17], 0, s[92:93]
	s_mov_b32 m0, s75
	s_addc_u32 s1, s47, 0
	global_load_lds_dwordx4 v[8:9], off
	s_add_i32 m0, s23, 0x1c000
	v_lshl_add_u64 v[8:9], s[0:1], 0, v[0:1]
	global_load_lds_dwordx4 v[8:9], off
	v_lshl_add_u64 v[8:9], s[0:1], 0, v[134:135]
	s_add_i32 m0, s23, 0x1e000
	v_or_b32_e32 v148, s20, v18
	global_load_lds_dwordx4 v[8:9], off
	s_waitcnt vmcnt(6)
	s_barrier
	v_lshlrev_b32_e32 v8, 15, v2
	v_and_b32_e32 v8, 0xffff0000, v8
	v_lshl_add_u32 v3, v3, 12, v8
	v_and_b32_e32 v2, 1, v2
	v_lshl_or_b32 v2, v2, 6, v3
	v_lshl_add_u32 v136, v4, 1, v2
	v_lshlrev_b32_e32 v2, 15, v5
	v_and_b32_e32 v2, 0xffff0000, v2
	s_waitcnt vmcnt(6)
	v_lshl_add_u32 v2, v6, 12, v2
	v_and_b32_e32 v3, 1, v5
	v_lshl_or_b32 v2, v3, 6, v2
	v_mov_b32_e32 v137, v1
	v_lshl_add_u32 v138, v7, 1, v2
	v_mov_b32_e32 v139, v1
	s_mov_b32 s76, 0
	v_add_u32_e32 v149, 0, v19
	s_barrier

; #define PG8_STAGE(bufoff, gbase, voff) do { _Pragma("unroll") for (int _i = 0; _i < 2; ++_i) \
;         __builtin_amdgcn_global_load_lds((const unsigned*)((const char*)(gbase) + (voff)[_i]), (LAS unsigned*)(lds + (bufoff) + ldsw + _i * 8192), 16, 0, 0); } while (0)
; #define PG8_WAIT_V(n) asm volatile("s_waitcnt vmcnt(" #n ")" ::: "memory")
; #define PG8_BAR __builtin_amdgcn_s_barrier()
; template <class Epi, class AMap>
; __device__ __forceinline__ void gemm_phase(LAS unsigned char* lds, const AMap am, const int lda, const h16* Bt, const int ldb, const int M, const int N, const int K, const Epi& E) {
;     ...
;     PG8_STAGE(PG8_SB(0, 0), cB, voffB); PG8_STAGE(PG8_SA(0, 0), cA, voffA); PG8_STAGE(PG8_SB(0, 1), cB + hstepB, voffB); PG8_STAGE(PG8_SA(0, 1), cA + hstepA, voffA);
;     if (wr == 1) PG8_BAR;
;     PG8_WAIT_V(4); PG8_BAR;
;     PG8_STAGE(PG8_SB(1, 0), cB + kstep, voffB); PG8_STAGE(PG8_SA(1, 0), cA + kstep, voffA); PG8_STAGE(PG8_SB(1, 1), cB + hstepB + kstep, voffB);
;     PG8_WAIT_V(6); PG8_BAR;
.LBB0_263:
	v_lshrrev_b32_e32 v16, 1, v0
	v_and_b32_e32 v17, 24, v16
	v_and_b32_e32 v148, 15, v0
	v_lshlrev_b32_e32 v18, 1, v17
	v_lshlrev_b32_e32 v19, 2, v0
	s_lshl_b32 s76, s0, 6
	v_lshl_or_b32 v18, v148, 6, v18
	s_lshl_b32 s0, s0, 13
	v_and_b32_e32 v19, 32, v19
	v_bitop3_b32 v20, v18, s0, v19 bitop3:0xde
	s_lshl_b32 s0, s1, 5
	s_and_b32 s20, s0, 0x60
	s_add_i32 m0, s72, 0x18000
	v_lshl_add_u64 v[8:9], v[8:9], 0, s[92:93]
	s_lshl_b32 s0, s20, 7
	global_load_lds_dwordx4 v[8:9], off
	v_lshl_add_u64 v[6:7], v[6:7], 0, s[92:93]
	s_add_i32 m0, s72, 0x1a000
	s_add_i32 s77, s72, 0x8000
	s_add_i32 s78, s72, 0xa000
	v_bitop3_b32 v149, v18, s0, v19 bitop3:0xde
	global_load_lds_dwordx4 v[6:7], off
	v_lshl_add_u64 v[4:5], v[4:5], 0, s[92:93]
	s_mov_b32 m0, s77
	s_add_u32 s0, s42, 0x80080
	global_load_lds_dwordx4 v[4:5], off
	v_lshl_add_u64 v[2:3], v[2:3], 0, s[92:93]
	s_mov_b32 m0, s78
	s_addc_u32 s1, s43, 0
	global_load_lds_dwordx4 v[2:3], off
	s_add_i32 m0, s72, 0x1c000
	v_lshl_add_u64 v[2:3], s[0:1], 0, v[132:133]
	global_load_lds_dwordx4 v[2:3], off
	v_lshl_add_u64 v[2:3], s[0:1], 0, v[136:137]
	s_add_i32 m0, s72, 0x1e000
	v_lshlrev_b32_e32 v0, 1, v0
	global_load_lds_dwordx4 v[2:3], off
	s_waitcnt vmcnt(6)
	s_barrier
	v_and_b32_e32 v2, 4, v16
	v_and_or_b32 v151, v0, 8, v2
	v_lshlrev_b32_e32 v0, 15, v10
	v_and_b32_e32 v0, 0xffff0000, v0
	v_lshl_add_u32 v0, v11, 12, v0
	v_and_b32_e32 v2, 1, v10
	v_lshl_or_b32 v0, v2, 6, v0
	v_lshl_add_u32 v138, v12, 1, v0
	v_lshlrev_b32_e32 v0, 15, v13
	v_and_b32_e32 v0, 0xffff0000, v0
	s_waitcnt vmcnt(6)
	v_lshl_add_u32 v0, v14, 12, v0
	v_and_b32_e32 v2, 1, v13
	v_or_b32_e32 v150, s20, v17
	v_lshl_or_b32 v0, v2, 6, v0
	v_or_b32_e32 v152, 0x80, v150
	v_mov_b32_e32 v139, v1
	v_lshl_add_u32 v140, v15, 1, v0
	v_mov_b32_e32 v141, v1
	s_mov_b32 s79, 0
	v_add_u32_e32 v153, 0, v20
	s_barrier
	s_branch .LBB0_265

; #define PG8_STAGE(bufoff, gbase, voff) do { _Pragma("unroll") for (int _i = 0; _i < 2; ++_i) \
;         __builtin_amdgcn_global_load_lds((const unsigned*)((const char*)(gbase) + (voff)[_i]), (LAS unsigned*)(lds + (bufoff) + ldsw + _i * 8192), 16, 0, 0); } while (0)
; #define PG8_WAIT_V(n) asm volatile("s_waitcnt vmcnt(" #n ")" ::: "memory")
; #define PG8_BAR __builtin_amdgcn_s_barrier()
; template <class Epi, class AMap>
; __device__ __forceinline__ void gemm_phase(LAS unsigned char* lds, const AMap am, const int lda, const h16* Bt, const int ldb, const int M, const int N, const int K, const Epi& E) {
;     ...
;     PG8_STAGE(PG8_SB(0, 0), cB, voffB); PG8_STAGE(PG8_SA(0, 0), cA, voffA); PG8_STAGE(PG8_SB(0, 1), cB + hstepB, voffB); PG8_STAGE(PG8_SA(0, 1), cA + hstepA, voffA);
;     if (wr == 1) PG8_BAR;
;     PG8_WAIT_V(4); PG8_BAR;
;     PG8_STAGE(PG8_SB(1, 0), cB + kstep, voffB); PG8_STAGE(PG8_SA(1, 0), cA + kstep, voffA); PG8_STAGE(PG8_SB(1, 1), cB + hstepB + kstep, voffB);
;     PG8_WAIT_V(6); PG8_BAR;
.LBB0_609:
	v_lshrrev_b32_e32 v20, 1, v18
	v_and_b32_e32 v20, 24, v20
	v_and_b32_e32 v19, 15, v18
	v_lshlrev_b32_e32 v21, 1, v20
	v_lshlrev_b32_e32 v18, 2, v18
	s_sext_i32_i8 s50, s0
	v_lshl_or_b32 v154, s20, 6, v19
	v_lshl_or_b32 v19, v19, 6, v21
	s_lshl_b32 s0, s20, 13
	v_and_b32_e32 v18, 32, v18
	v_bitop3_b32 v21, v19, s0, v18 bitop3:0xde
	s_lshl_b32 s0, s1, 5
	s_and_b32 s20, s0, 0x60
	s_lshl_b32 s0, s20, 7
	v_bitop3_b32 v155, v19, s0, v18 bitop3:0xde
	v_readlane_b32 s0, v254, 38
	v_readlane_b32 s10, v254, 48
	v_readlane_b32 s11, v254, 49
	s_add_u32 s40, s10, s46
	s_addc_u32 s41, s11, s47
	s_add_i32 m0, s76, 0x18000
	v_lshl_add_u64 v[8:9], v[8:9], 0, s[92:93]
	global_load_lds_dwordx4 v[8:9], off
	v_lshl_add_u64 v[6:7], v[6:7], 0, s[92:93]
	s_add_i32 m0, s76, 0x1a000
	s_add_i32 s80, s76, 0x8000
	s_add_i32 s81, s76, 0xa000
	v_readlane_b32 s1, v254, 39
	global_load_lds_dwordx4 v[6:7], off
	v_lshl_add_u64 v[4:5], v[4:5], 0, s[92:93]
	s_mov_b32 m0, s80
	s_add_u32 s0, s26, 0x10080
	global_load_lds_dwordx4 v[4:5], off
	v_lshl_add_u64 v[2:3], v[2:3], 0, s[92:93]
	s_mov_b32 m0, s81
	s_addc_u32 s1, s27, 0
	global_load_lds_dwordx4 v[2:3], off
	s_add_i32 m0, s76, 0x1c000
	v_lshl_add_u64 v[2:3], s[0:1], 0, v[0:1]
	global_load_lds_dwordx4 v[2:3], off
	v_lshl_add_u64 v[2:3], s[0:1], 0, v[142:143]
	s_add_i32 m0, s76, 0x1e000
	v_readlane_b32 s3, v254, 41
	global_load_lds_dwordx4 v[2:3], off
	s_waitcnt vmcnt(6)
	s_barrier
	v_readlane_b32 s2, v254, 40
	s_movk_i32 s3, 0x1c00
	v_lshrrev_b32_e32 v3, 1, v10
	v_mul_lo_u32 v2, v12, s3
	s_mov_b32 s2, 0x1c000
	v_mad_u64_u32 v[2:3], s[0:1], v3, s2, v[2:3]
	v_readlane_b32 s4, v254, 42
	v_readlane_b32 s5, v254, 43
	v_or_b32_e32 v2, v2, v11
	v_add_lshl_u32 v2, v2, v13, 1
	v_mov_b32_e32 v3, v1
	s_mov_b64 s[4:5], 0x1c0080
	v_lshl_add_u64 v[144:145], v[2:3], 0, s[4:5]
	v_lshrrev_b32_e32 v3, 1, v14
	v_mul_lo_u32 v2, v16, s3
	v_mad_u64_u32 v[2:3], s[0:1], v3, s2, v[2:3]
	v_readlane_b32 s8, v254, 46
	v_readlane_b32 s9, v254, 47
	s_waitcnt vmcnt(6)
	v_or_b32_e32 v2, v2, v15
	v_readlane_b32 s12, v254, 50
	v_readlane_b32 s13, v254, 51
	v_readlane_b32 s14, v254, 52
	v_readlane_b32 s15, v254, 53
	s_cmp_gt_i32 s61, 63
	v_add_lshl_u32 v2, v2, v17, 1
	v_mov_b32_e32 v3, v1
	v_readlane_b32 s8, v254, 58
	s_cselect_b64 s[42:43], -1, 0
	s_add_i32 s82, s24, -2
	v_or_b32_e32 v156, s20, v20
	v_lshl_add_u64 v[146:147], v[2:3], 0, s[4:5]
	s_mov_b32 s83, 0
	v_add_u32_e32 v157, 0, v21
	v_readlane_b32 s9, v254, 59
	v_readlane_b32 s12, v254, 62
	v_readlane_b32 s2, v252, 33
	s_movk_i32 s5, 0x3800
	s_movk_i32 s13, 0x2b00
	s_mov_b64 s[10:11], 0x80000
	s_mov_b64 s[14:15], 0xa0000
	v_readlane_b32 s6, v254, 44
	v_readlane_b32 s7, v254, 45
	s_barrier
	s_branch .LBB0_611

; #define PG8_STAGE(bufoff, gbase, voff) do { _Pragma("unroll") for (int _i = 0; _i < 2; ++_i) \
;         __builtin_amdgcn_global_load_lds((const unsigned*)((const char*)(gbase) + (voff)[_i]), (LAS unsigned*)(lds + (bufoff) + ldsw + _i * 8192), 16, 0, 0); } while (0)
; #define PG8_WAIT_V(n) asm volatile("s_waitcnt vmcnt(" #n ")" ::: "memory")
; #define PG8_BAR __builtin_amdgcn_s_barrier()
; template <class Epi, class AMap>
; __device__ __forceinline__ void gemm_phase(LAS unsigned char* lds, const AMap am, const int lda, const h16* Bt, const int ldb, const int M, const int N, const int K, const Epi& E) {
;     ...
;     PG8_STAGE(PG8_SB(0, 0), cB, voffB); PG8_STAGE(PG8_SA(0, 0), cA, voffA); PG8_STAGE(PG8_SB(0, 1), cB + hstepB, voffB); PG8_STAGE(PG8_SA(0, 1), cA + hstepA, voffA);
;     if (wr == 1) PG8_BAR;
;     PG8_WAIT_V(4); PG8_BAR;
;     PG8_STAGE(PG8_SB(1, 0), cB + kstep, voffB); PG8_STAGE(PG8_SA(1, 0), cA + kstep, voffA); PG8_STAGE(PG8_SB(1, 1), cB + hstepB + kstep, voffB);
;     PG8_WAIT_V(6); PG8_BAR;
.LBB0_632:
	v_lshrrev_b32_e32 v20, 1, v18
	v_and_b32_e32 v20, 24, v20
	v_and_b32_e32 v19, 15, v18
	v_lshlrev_b32_e32 v21, 1, v20
	v_lshlrev_b32_e32 v18, 2, v18
	s_sext_i32_i8 s50, s0
	s_and_b32 s20, s20, 3
	v_lshl_or_b32 v202, s1, 6, v19
	v_lshl_or_b32 v19, v19, 6, v21
	s_lshl_b32 s0, s1, 13
	v_and_b32_e32 v18, 32, v18
	v_bitop3_b32 v21, v19, s0, v18 bitop3:0xde
	s_lshl_b32 s0, s20, 12
	v_bitop3_b32 v203, v19, s0, v18 bitop3:0xde
	v_readlane_b32 s0, v251, 37
	v_readlane_b32 s1, v251, 38
	s_add_u32 s40, s0, s46
	s_addc_u32 s41, s1, s47
	s_add_i32 m0, s74, 0x18000
	v_lshl_add_u64 v[8:9], v[8:9], 0, s[92:93]
	global_load_lds_dwordx4 v[8:9], off
	v_lshl_add_u64 v[6:7], v[6:7], 0, s[92:93]
	s_add_i32 m0, s74, 0x1a000
	s_add_i32 s78, s74, 0x8000
	s_add_i32 s79, s74, 0xa000
	global_load_lds_dwordx4 v[6:7], off
	v_lshl_add_u64 v[4:5], v[4:5], 0, s[92:93]
	s_mov_b32 m0, s78
	s_add_u32 s0, s26, 0x10080
	global_load_lds_dwordx4 v[4:5], off
	v_lshl_add_u64 v[2:3], v[2:3], 0, s[92:93]
	s_mov_b32 m0, s79
	s_addc_u32 s1, s27, 0
	global_load_lds_dwordx4 v[2:3], off
	s_add_i32 m0, s74, 0x1c000
	v_lshl_add_u64 v[2:3], s[0:1], 0, v[0:1]
	global_load_lds_dwordx4 v[2:3], off
	v_lshl_add_u64 v[2:3], s[0:1], 0, v[146:147]
	s_add_i32 m0, s74, 0x1e000
	v_readlane_b32 s3, v251, 40
	global_load_lds_dwordx4 v[2:3], off
	s_waitcnt vmcnt(6)
	s_barrier
	v_readlane_b32 s2, v251, 39
	s_movk_i32 s3, 0x1c00
	v_lshrrev_b32_e32 v3, 1, v10
	v_mul_lo_u32 v2, v12, s3
	s_mov_b32 s2, 0x1c000
	v_mad_u64_u32 v[2:3], s[0:1], v3, s2, v[2:3]
	v_readlane_b32 s4, v251, 41
	v_readlane_b32 s5, v251, 42
	v_or_b32_e32 v2, v2, v11
	v_add_lshl_u32 v2, v2, v13, 1
	v_mov_b32_e32 v3, v1
	s_mov_b64 s[4:5], 0x1c0080
	v_lshl_add_u64 v[148:149], v[2:3], 0, s[4:5]
	v_lshrrev_b32_e32 v3, 1, v14
	v_mul_lo_u32 v2, v16, s3
	v_mad_u64_u32 v[2:3], s[0:1], v3, s2, v[2:3]
	v_readlane_b32 s8, v251, 45
	v_readlane_b32 s9, v251, 46
	s_waitcnt vmcnt(6)
	v_or_b32_e32 v2, v2, v15
	v_readlane_b32 s12, v251, 49
	v_readlane_b32 s13, v251, 50
	v_readlane_b32 s14, v251, 51
	v_readlane_b32 s15, v251, 52
	s_cmp_gt_i32 s61, 63
	v_add_lshl_u32 v2, v2, v17, 1
	v_mov_b32_e32 v3, v1
	v_readlane_b32 s8, v254, 58
	v_readlane_b32 s2, v251, 7
	s_cselect_b64 s[42:43], -1, 0
	s_add_i32 s80, s24, -2
	v_lshl_or_b32 v204, s20, 6, v20
	v_lshl_add_u64 v[150:151], v[2:3], 0, s[4:5]
	s_mov_b32 s81, 0
	v_add_u32_e32 v205, 0, v21
	v_readlane_b32 s9, v254, 59
	v_readlane_b32 s3, v251, 8
	v_readlane_b32 s12, v254, 62
	s_movk_i32 s5, 0x3800
	s_movk_i32 s13, 0x2b00
	s_mov_b64 s[14:15], 0xa0000
	v_readlane_b32 s6, v251, 43
	v_readlane_b32 s7, v251, 44
	v_readlane_b32 s10, v251, 47
	v_readlane_b32 s11, v251, 48
	s_barrier
	s_branch .LBB0_634

; #define PG8_STAGE(bufoff, gbase, voff) do { _Pragma("unroll") for (int _i = 0; _i < 2; ++_i) \
;         __builtin_amdgcn_global_load_lds((const unsigned*)((const char*)(gbase) + (voff)[_i]), (LAS unsigned*)(lds + (bufoff) + ldsw + _i * 8192), 16, 0, 0); } while (0)
; #define PG8_WAIT_V(n) asm volatile("s_waitcnt vmcnt(" #n ")" ::: "memory")
; #define PG8_BAR __builtin_amdgcn_s_barrier()
; template <class Epi, class AMap>
; __device__ __forceinline__ void gemm_phase(LAS unsigned char* lds, const AMap am, const int lda, const h16* Bt, const int ldb, const int M, const int N, const int K, const Epi& E) {
;     ...
;     PG8_STAGE(PG8_SB(0, 0), cB, voffB); PG8_STAGE(PG8_SA(0, 0), cA, voffA); PG8_STAGE(PG8_SB(0, 1), cB + hstepB, voffB); PG8_STAGE(PG8_SA(0, 1), cA + hstepA, voffA);
;     if (wr == 1) PG8_BAR;
;     PG8_WAIT_V(4); PG8_BAR;
;     PG8_STAGE(PG8_SB(1, 0), cB + kstep, voffB); PG8_STAGE(PG8_SA(1, 0), cA + kstep, voffA); PG8_STAGE(PG8_SB(1, 1), cB + hstepB + kstep, voffB);
;     PG8_WAIT_V(6); PG8_BAR;
.LBB0_655:
	v_lshrrev_b32_e32 v20, 1, v18
	v_and_b32_e32 v20, 24, v20
	v_and_b32_e32 v19, 15, v18
	v_lshlrev_b32_e32 v21, 1, v20
	v_lshlrev_b32_e32 v18, 2, v18
	s_sext_i32_i8 s76, s0
	v_lshl_or_b32 v160, s20, 6, v19
	v_lshl_or_b32 v19, v19, 6, v21
	s_lshl_b32 s0, s20, 13
	v_and_b32_e32 v18, 32, v18
	v_bitop3_b32 v21, v19, s0, v18 bitop3:0xde
	s_lshl_b32 s0, s1, 5
	s_and_b32 s20, s0, 0x60
	s_add_i32 m0, s65, 0x18000
	v_lshl_add_u64 v[8:9], v[8:9], 0, s[92:93]
	s_lshl_b32 s0, s20, 7
	global_load_lds_dwordx4 v[8:9], off
	v_lshl_add_u64 v[6:7], v[6:7], 0, s[92:93]
	s_add_i32 m0, s65, 0x1a000
	s_add_i32 s71, s65, 0x8000
	s_add_i32 s72, s65, 0xa000
	v_bitop3_b32 v161, v19, s0, v18 bitop3:0xde
	global_load_lds_dwordx4 v[6:7], off
	v_lshl_add_u64 v[4:5], v[4:5], 0, s[92:93]
	s_mov_b32 m0, s71
	s_add_u32 s0, s46, 0x10080
	global_load_lds_dwordx4 v[4:5], off
	v_lshl_add_u64 v[2:3], v[2:3], 0, s[92:93]
	s_mov_b32 m0, s72
	s_addc_u32 s1, s47, 0
	global_load_lds_dwordx4 v[2:3], off
	s_add_i32 m0, s65, 0x1c000
	v_lshl_add_u64 v[2:3], s[0:1], 0, v[0:1]
	global_load_lds_dwordx4 v[2:3], off
	v_lshl_add_u64 v[2:3], s[0:1], 0, v[134:135]
	s_add_i32 m0, s65, 0x1e000
	s_movk_i32 s6, 0x1c00
	global_load_lds_dwordx4 v[2:3], off
	s_waitcnt vmcnt(6)
	s_barrier
	v_lshrrev_b32_e32 v3, 1, v10
	v_mul_lo_u32 v2, v12, s6
	s_mov_b32 s4, 0x1c000
	v_mad_u64_u32 v[2:3], s[0:1], v3, s4, v[2:3]
	v_or_b32_e32 v2, v2, v11
	v_or_b32_e32 v162, s20, v20
	v_add_lshl_u32 v2, v2, v13, 1
	v_mov_b32_e32 v3, v1
	s_mov_b64 s[20:21], 0x1c0080
	v_lshl_add_u64 v[136:137], v[2:3], 0, s[20:21]
	v_lshrrev_b32_e32 v3, 1, v14
	v_mul_lo_u32 v2, v16, s6
	v_mad_u64_u32 v[2:3], s[0:1], v3, s4, v[2:3]
	s_waitcnt vmcnt(6)
	v_or_b32_e32 v2, v2, v15
	s_cmp_gt_i32 s61, 63
	v_add_lshl_u32 v2, v2, v17, 1
	v_mov_b32_e32 v3, v1
	s_cselect_b64 s[22:23], -1, 0
	s_add_i32 s73, s24, -2
	v_lshl_add_u64 v[138:139], v[2:3], 0, s[20:21]
	s_mov_b32 s75, 0
	v_add_u32_e32 v163, 0, v21
	s_barrier
	s_branch .LBB0_657

; #define PG8_STAGE(bufoff, gbase, voff) do { _Pragma("unroll") for (int _i = 0; _i < 2; ++_i) \
;         __builtin_amdgcn_global_load_lds((const unsigned*)((const char*)(gbase) + (voff)[_i]), (LAS unsigned*)(lds + (bufoff) + ldsw + _i * 8192), 16, 0, 0); } while (0)
; #define PG8_WAIT_V(n) asm volatile("s_waitcnt vmcnt(" #n ")" ::: "memory")
; #define PG8_BAR __builtin_amdgcn_s_barrier()
; template <class Epi, class AMap>
; __device__ __forceinline__ void gemm_phase(LAS unsigned char* lds, const AMap am, const int lda, const h16* Bt, const int ldb, const int M, const int N, const int K, const Epi& E) {
;     ...
;     PG8_STAGE(PG8_SB(0, 0), cB, voffB); PG8_STAGE(PG8_SA(0, 0), cA, voffA); PG8_STAGE(PG8_SB(0, 1), cB + hstepB, voffB); PG8_STAGE(PG8_SA(0, 1), cA + hstepA, voffA);
;     if (wr == 1) PG8_BAR;
;     PG8_WAIT_V(4); PG8_BAR;
;     PG8_STAGE(PG8_SB(1, 0), cB + kstep, voffB); PG8_STAGE(PG8_SA(1, 0), cA + kstep, voffA); PG8_STAGE(PG8_SB(1, 1), cB + hstepB + kstep, voffB);
;     PG8_WAIT_V(6); PG8_BAR;
.LBB0_680:
	v_lshrrev_b32_e32 v20, 1, v18
	v_and_b32_e32 v20, 24, v20
	v_and_b32_e32 v19, 15, v18
	v_lshlrev_b32_e32 v21, 1, v20
	v_lshlrev_b32_e32 v18, 2, v18
	s_sext_i32_i8 s50, s0
	v_lshl_or_b32 v174, s20, 6, v19
	v_lshl_or_b32 v19, v19, 6, v21
	s_lshl_b32 s0, s20, 13
	v_and_b32_e32 v18, 32, v18
	v_bitop3_b32 v21, v19, s0, v18 bitop3:0xde
	s_lshl_b32 s0, s1, 5
	s_and_b32 s20, s0, 0x60
	s_lshl_b32 s0, s20, 7
	v_bitop3_b32 v175, v19, s0, v18 bitop3:0xde
	v_readlane_b32 s0, v255, 7
	v_readlane_b32 s1, v255, 8
	s_mov_b32 s1, s25
	s_lshl_b64 s[0:1], s[0:1], 11
	s_add_u32 s21, s0, 0xfffff800
	s_addc_u32 s29, s1, -1
	s_and_b64 s[0:1], s[82:83], exec
	s_cselect_b32 s1, 0, s29
	s_cselect_b32 s0, 0, s21
	v_readlane_b32 s4, v251, 37
	s_lshl_b64 s[0:1], s[0:1], 2
	v_readlane_b32 s10, v251, 43
	v_readlane_b32 s11, v251, 44
	s_add_u32 s40, s10, s0
	s_addc_u32 s41, s11, s1
	s_add_i32 m0, s74, 0x18000
	v_lshl_add_u64 v[8:9], v[8:9], 0, s[92:93]
	global_load_lds_dwordx4 v[8:9], off
	v_lshl_add_u64 v[6:7], v[6:7], 0, s[92:93]
	s_add_i32 m0, s74, 0x1a000
	s_add_i32 s79, s74, 0x8000
	s_add_i32 s80, s74, 0xa000
	global_load_lds_dwordx4 v[6:7], off
	v_lshl_add_u64 v[4:5], v[4:5], 0, s[92:93]
	s_mov_b32 m0, s79
	s_add_u32 s0, s26, 0x10080
	global_load_lds_dwordx4 v[4:5], off
	v_lshl_add_u64 v[2:3], v[2:3], 0, s[92:93]
	s_mov_b32 m0, s80
	s_addc_u32 s1, s27, 0
	global_load_lds_dwordx4 v[2:3], off
	s_add_i32 m0, s74, 0x1c000
	v_lshl_add_u64 v[2:3], s[0:1], 0, v[0:1]
	global_load_lds_dwordx4 v[2:3], off
	v_lshl_add_u64 v[2:3], s[0:1], 0, v[150:151]
	s_add_i32 m0, s74, 0x1e000
	v_readlane_b32 s5, v251, 38
	global_load_lds_dwordx4 v[2:3], off
	s_waitcnt vmcnt(6)
	s_barrier
	s_movk_i32 s5, 0x1c00
	v_lshrrev_b32_e32 v3, 1, v10
	v_mul_lo_u32 v2, v12, s5
	s_mov_b32 s4, 0x1c000
	v_mad_u64_u32 v[2:3], s[0:1], v3, s4, v[2:3]
	v_readlane_b32 s6, v251, 39
	v_readlane_b32 s7, v251, 40
	v_or_b32_e32 v2, v2, v11
	v_add_lshl_u32 v2, v2, v13, 1
	v_mov_b32_e32 v3, v1
	s_mov_b64 s[6:7], 0x1c0080
	v_lshl_add_u64 v[152:153], v[2:3], 0, s[6:7]
	v_lshrrev_b32_e32 v3, 1, v14
	v_mul_lo_u32 v2, v16, s5
	v_mad_u64_u32 v[2:3], s[0:1], v3, s4, v[2:3]
	v_readlane_b32 s8, v251, 41
	v_readlane_b32 s9, v251, 42
	s_waitcnt vmcnt(6)
	v_or_b32_e32 v2, v2, v15
	v_readlane_b32 s12, v251, 45
	v_readlane_b32 s13, v251, 46
	s_cmp_gt_i32 s61, 63
	v_add_lshl_u32 v2, v2, v17, 1
	v_mov_b32_e32 v3, v1
	v_readlane_b32 s8, v254, 58
	s_mov_b32 s78, 0
	s_cselect_b64 s[42:43], -1, 0
	s_add_i32 s61, s24, -2
	v_or_b32_e32 v176, s20, v20
	v_lshl_add_u64 v[154:155], v[2:3], 0, s[6:7]
	v_add_u32_e32 v177, 0, v21
	v_readlane_b32 s9, v254, 59
	v_readlane_b32 s12, v254, 62
	s_movk_i32 s5, 0x3800
	s_movk_i32 s13, 0x2b00
	v_readlane_b32 s14, v251, 47
	v_readlane_b32 s15, v251, 48
	v_readlane_b32 s16, v251, 49
	v_readlane_b32 s17, v251, 50
	v_readlane_b32 s18, v251, 51
	v_readlane_b32 s19, v251, 52
	s_barrier
	s_branch .LBB0_682

; #define PG8_STAGE(bufoff, gbase, voff) do { _Pragma("unroll") for (int _i = 0; _i < 2; ++_i) \
;         __builtin_amdgcn_global_load_lds((const unsigned*)((const char*)(gbase) + (voff)[_i]), (LAS unsigned*)(lds + (bufoff) + ldsw + _i * 8192), 16, 0, 0); } while (0)
; #define PG8_WAIT_V(n) asm volatile("s_waitcnt vmcnt(" #n ")" ::: "memory")
; #define PG8_BAR __builtin_amdgcn_s_barrier()
; template <class Epi, class AMap>
; __device__ __forceinline__ void gemm_phase(LAS unsigned char* lds, const AMap am, const int lda, const h16* Bt, const int ldb, const int M, const int N, const int K, const Epi& E) {
;     ...
;     PG8_STAGE(PG8_SB(0, 0), cB, voffB); PG8_STAGE(PG8_SA(0, 0), cA, voffA); PG8_STAGE(PG8_SB(0, 1), cB + hstepB, voffB); PG8_STAGE(PG8_SA(0, 1), cA + hstepA, voffA);
;     if (wr == 1) PG8_BAR;
;     PG8_WAIT_V(4); PG8_BAR;
;     PG8_STAGE(PG8_SB(1, 0), cB + kstep, voffB); PG8_STAGE(PG8_SA(1, 0), cA + kstep, voffA); PG8_STAGE(PG8_SB(1, 1), cB + hstepB + kstep, voffB);
;     PG8_WAIT_V(6); PG8_BAR;
.LBB0_780:
	v_lshrrev_b32_e32 v18, 1, v2
	v_and_b32_e32 v18, 24, v18
	v_and_b32_e32 v9, 15, v2
	v_lshlrev_b32_e32 v19, 1, v18
	v_lshlrev_b32_e32 v2, 2, v2
	v_lshl_or_b32 v154, s20, 6, v9
	v_lshl_or_b32 v9, v9, 6, v19
	s_lshl_b32 s0, s20, 13
	v_and_b32_e32 v2, 32, v2
	v_lshl_add_u64 v[10:11], s[40:41], 0, v[0:1]
	v_mov_b32_e32 v143, v1
	v_bitop3_b32 v19, v9, s0, v2 bitop3:0xde
	s_lshl_b32 s0, s21, 5
	v_lshl_add_u64 v[12:13], s[40:41], 0, v[142:143]
	v_mov_b32_e32 v139, v1
	s_and_b32 s20, s0, 0x60
	s_add_i32 m0, s23, 0x18000
	v_lshl_add_u64 v[10:11], v[10:11], 0, s[92:93]
	v_lshl_add_u64 v[14:15], s[48:49], 0, v[138:139]
	v_mov_b32_e32 v141, v1
	s_lshl_b32 s0, s20, 7
	global_load_lds_dwordx4 v[10:11], off
	v_lshl_add_u64 v[10:11], v[12:13], 0, s[92:93]
	s_add_i32 m0, s23, 0x1a000
	s_add_i32 s75, s23, 0x8000
	s_add_i32 s76, s23, 0xa000
	v_lshl_add_u64 v[16:17], s[48:49], 0, v[140:141]
	v_bitop3_b32 v155, v9, s0, v2 bitop3:0xde
	global_load_lds_dwordx4 v[10:11], off
	v_lshl_add_u64 v[10:11], v[14:15], 0, s[92:93]
	s_mov_b32 m0, s75
	s_add_u32 s0, s40, 0x80080
	global_load_lds_dwordx4 v[10:11], off
	v_lshl_add_u64 v[10:11], v[16:17], 0, s[92:93]
	s_mov_b32 m0, s76
	s_addc_u32 s1, s41, 0
	global_load_lds_dwordx4 v[10:11], off
	s_add_i32 m0, s23, 0x1c000
	v_lshl_add_u64 v[10:11], s[0:1], 0, v[0:1]
	global_load_lds_dwordx4 v[10:11], off
	v_lshl_add_u64 v[10:11], s[0:1], 0, v[142:143]
	s_add_i32 m0, s23, 0x1e000
	v_cvt_f32_ubyte0_e32 v2, s68
	global_load_lds_dwordx4 v[10:11], off
	s_waitcnt vmcnt(6)
	s_barrier
	v_rcp_iflag_f32_e32 v2, v2
	s_sub_i32 s0, 0, s68
	s_waitcnt vmcnt(6)
	v_or_b32_e32 v156, s20, v18
	v_mul_f32_e32 v2, 0x4f7ffffe, v2
	v_cvt_u32_f32_e32 v2, v2
	s_mov_b32 s77, 0
	v_mov_b32_e32 v145, v1
	v_mov_b32_e32 v147, v1
	v_readfirstlane_b32 s1, v2
	v_lshlrev_b32_e32 v2, 15, v3
	v_and_b32_e32 v2, 0xffff0000, v2
	v_lshl_add_u32 v2, v4, 12, v2
	v_and_b32_e32 v3, 1, v3
	v_lshl_or_b32 v2, v3, 6, v2
	v_lshl_add_u32 v144, v5, 1, v2
	v_lshlrev_b32_e32 v2, 15, v6
	v_and_b32_e32 v2, 0xffff0000, v2
	s_mul_i32 s0, s0, s1
	v_lshl_add_u32 v2, v7, 12, v2
	v_and_b32_e32 v3, 1, v6
	s_mul_hi_u32 s0, s1, s0
	v_lshl_or_b32 v2, v3, 6, v2
	s_add_i32 s78, s1, s0
	v_lshl_add_u32 v146, v8, 1, v2
	v_add_u32_e32 v157, 0, v19
	s_barrier
	s_branch .LBB0_782
